# ret_out epilogue: readers renamed to the prefetch registers, 96 v_mov copies per unit removed, on top of v068
# baseline (speedup 1.0000x reference)
; #define LAS __attribute__((address_space(3)))
; #define LDS_WAIT() asm volatile("s_waitcnt lgkmcnt(0)" ::: "memory")
; __device__ __forceinline__ unsigned cvt_pk_bf16(float lo, float hi) { f32x2 v = {lo, hi}; bf16v2_t r = __builtin_convertvector(v, bf16v2_t); return __builtin_bit_cast(unsigned, r); }
; __device__ __forceinline__ float shfl_xor_(float v, int m) { return __builtin_bit_cast(float, __builtin_amdgcn_ds_bpermute((lane_id() ^ m) << 2, __builtin_bit_cast(int, v))); }
; __device__ __forceinline__ void phase_ret_out(const Frame& F, const Args& a, int l) {
;     ...
;         s1 += shfl_xor_(s1, 32); s2 += shfl_xor_(s2, 32);
;         if (hh == 0) SX[(dj * 4 + qi) * 32 + li] = (f32x2){s1, s2};
;         LDS_WAIT(); __syncthreads();
;         { const f32x2 ot = SX[((dj ^ 1) * 4 + qi) * 32 + li]; s1 += ot.x; s2 += ot.y; }
;         const float mu = s1 * (1.0f / 256.0f); const float var = fmaxf(s2 * (1.0f / 256.0f) - mu * mu, 0.f); const float rstd = 1.0f / sqrtf(var + 1e-5f);
; #pragma unroll
;         for (int dt = 0; dt < 4; ++dt)
; #pragma unroll
;             for (int q4 = 0; q4 < 4; ++q4) { v2u pw; pw.x = cvt_pk_bf16((o[dt][4 * q4] - mu) * rstd, (o[dt][4 * q4 + 1] - mu) * rstd); pw.y = cvt_pk_bf16((o[dt][4 * q4 + 2] - mu) * rstd, (o[dt][4 * q4 + 3] - mu) * rstd);
;                 *(LAS v2u*)(stg + li * PLD + (32 * dt + 8 * q4 + 4 * hh) * 2) = pw; }
;     ...
;             const int idx = lane + 64 * j, q = idx >> 4, cv = idx & 15, col = h * 256 + 128 * dj + 8 * cv;
;             const v4u ov = *(const LAS v4u*)(stg + q * PLD + cv * 16);
;             const size_t tok = tok0 + 32 * qi + q;
;             const v4u gv = *(const v4u*)(RG + tok * 1024 + col);
;             const f32x4 r0 = *(const f32x4*)(rn + col), r1 = *(const f32x4*)(rn + col + 4);
.LBB0_1205:
	s_or_b64 exec, exec, s[6:7]
	v_lshl_add_u32 v172, s23, 8, v117
	v_ashrrev_i32_e32 v173, 31, v172
	v_lshlrev_b64 v[174:175], 1, v[172:173]
	v_lshl_add_u64 v[178:179], v[172:173], 2, s[18:19]
	v_lshl_add_u64 v[176:177], s[12:13], 0, v[174:175]
	global_load_dwordx4 v[164:167], v[178:179], off
	global_load_dwordx4 v[168:171], v[178:179], off offset:16
	v_mov_b32_e32 v181, s25
	v_or_b32_e32 v180, s24, v110
	v_lshlrev_b64 v[180:181], 11, v[180:181]
	v_lshl_add_u64 v[180:181], v[176:177], 0, v[180:181]
	global_load_dwordx4 v[132:135], v[180:181], off
	v_mov_b32_e32 v183, s25
	v_or_b32_e32 v182, s24, v112
	v_lshlrev_b64 v[182:183], 11, v[182:183]
	v_lshl_add_u64 v[182:183], v[176:177], 0, v[182:183]
	global_load_dwordx4 v[136:139], v[182:183], off
	v_mov_b32_e32 v181, s25
	v_or_b32_e32 v180, s24, v114
	v_lshlrev_b64 v[180:181], 11, v[180:181]
	v_lshl_add_u64 v[180:181], v[176:177], 0, v[180:181]
	global_load_dwordx4 v[140:143], v[180:181], off
	v_mov_b32_e32 v183, s25
	v_or_b32_e32 v182, s24, v116
	v_lshlrev_b64 v[182:183], 11, v[182:183]
	v_lshl_add_u64 v[182:183], v[176:177], 0, v[182:183]
	global_load_dwordx4 v[144:147], v[182:183], off
	v_mov_b32_e32 v181, s25
	v_or_b32_e32 v180, s24, v118
	v_lshlrev_b64 v[180:181], 11, v[180:181]
	v_lshl_add_u64 v[180:181], v[176:177], 0, v[180:181]
	global_load_dwordx4 v[148:151], v[180:181], off
	v_mov_b32_e32 v183, s25
	v_or_b32_e32 v182, s24, v120
	v_lshlrev_b64 v[182:183], 11, v[182:183]
	v_lshl_add_u64 v[182:183], v[176:177], 0, v[182:183]
	global_load_dwordx4 v[152:155], v[182:183], off
	v_mov_b32_e32 v181, s25
	v_or_b32_e32 v180, s24, v122
	v_lshlrev_b64 v[180:181], 11, v[180:181]
	v_lshl_add_u64 v[180:181], v[176:177], 0, v[180:181]
	global_load_dwordx4 v[156:159], v[180:181], off
	v_mov_b32_e32 v183, s25
	v_or_b32_e32 v182, s24, v124
	v_lshlrev_b64 v[182:183], 11, v[182:183]
	v_lshl_add_u64 v[182:183], v[176:177], 0, v[182:183]
	global_load_dwordx4 v[160:163], v[182:183], off
	s_waitcnt lgkmcnt(0)
	s_waitcnt lgkmcnt(0)
	s_barrier
	ds_read_b64 v[66:67], v115 offset:34816
	s_mov_b32 s6, 0x3b800000
	s_add_i32 s29, s29, s28
	s_cmpk_lt_i32 s29, 0x500
	s_waitcnt lgkmcnt(0)
	v_pk_add_f32 v[64:65], v[64:65], v[66:67]
	s_nop 0
	v_pk_mul_f32 v[64:65], v[64:65], s[6:7] op_sel_hi:[1,0]
	s_nop 0
	v_fma_f32 v66, -v64, v64, v65
	v_max_f32_e32 v66, 0, v66
	v_add_f32_e32 v66, 0x3727c5ac, v66
	v_mul_f32_e32 v67, 0x4f800000, v66
	v_cmp_gt_f32_e32 vcc, s86, v66
	v_pk_add_f32 v[0:1], v[0:1], v[64:65] op_sel_hi:[1,0] neg_lo:[0,1] neg_hi:[0,1]
	v_pk_add_f32 v[2:3], v[2:3], v[64:65] op_sel_hi:[1,0] neg_lo:[0,1] neg_hi:[0,1]
	v_cndmask_b32_e32 v66, v66, v67, vcc
	v_sqrt_f32_e32 v67, v66
	s_nop 0
	v_add_u32_e32 v68, -1, v67
	v_fma_f32 v70, -v68, v67, v66
	v_add_u32_e32 v69, 1, v67
	v_cmp_ge_f32_e64 s[6:7], 0, v70
	s_nop 1
	v_cndmask_b32_e64 v68, v67, v68, s[6:7]
	v_fma_f32 v67, -v69, v67, v66
	v_cmp_lt_f32_e64 s[6:7], 0, v67
	s_nop 1
	v_cndmask_b32_e64 v67, v68, v69, s[6:7]
	v_mul_f32_e32 v68, 0x37800000, v67
	v_cndmask_b32_e32 v67, v67, v68, vcc
	v_cmp_class_f32_e32 vcc, v66, v204
	s_nop 1
	v_cndmask_b32_e32 v66, v67, v66, vcc
	v_div_scale_f32 v67, s[6:7], v66, v66, 1.0
	v_rcp_f32_e32 v68, v67
	s_nop 0
	v_fma_f32 v69, -v67, v68, 1.0
	v_fmac_f32_e32 v68, v69, v68
	v_div_scale_f32 v69, vcc, 1.0, v66, 1.0
	v_mul_f32_e32 v70, v69, v68
	v_fma_f32 v71, -v67, v70, v69
	v_fmac_f32_e32 v70, v71, v68
	v_fma_f32 v67, -v67, v70, v69
	v_div_fmas_f32 v67, v67, v68, v70
	v_div_fixup_f32 v66, v67, v66, 1.0
	v_pk_mul_f32 v[0:1], v[0:1], v[66:67] op_sel_hi:[1,0]
	v_pk_mul_f32 v[2:3], v[2:3], v[66:67] op_sel_hi:[1,0]
	v_cvt_pk_bf16_f32 v0, v0, v1
	v_cvt_pk_bf16_f32 v1, v2, v3
	v_pk_add_f32 v[2:3], v[4:5], v[64:65] op_sel_hi:[1,0] neg_lo:[0,1] neg_hi:[0,1]
	v_pk_add_f32 v[4:5], v[6:7], v[64:65] op_sel_hi:[1,0] neg_lo:[0,1] neg_hi:[0,1]
	v_pk_mul_f32 v[2:3], v[2:3], v[66:67] op_sel_hi:[1,0]
	v_pk_mul_f32 v[4:5], v[4:5], v[66:67] op_sel_hi:[1,0]
	v_cvt_pk_bf16_f32 v2, v2, v3
	v_cvt_pk_bf16_f32 v3, v4, v5
	v_add_u32_e32 v6, 0xa000, v125
	ds_write2_b64 v6, v[0:1], v[2:3] offset1:2
	v_pk_add_f32 v[0:1], v[8:9], v[64:65] op_sel_hi:[1,0] neg_lo:[0,1] neg_hi:[0,1]
	v_pk_add_f32 v[2:3], v[10:11], v[64:65] op_sel_hi:[1,0] neg_lo:[0,1] neg_hi:[0,1]
	v_pk_mul_f32 v[0:1], v[0:1], v[66:67] op_sel_hi:[1,0]
	v_pk_mul_f32 v[2:3], v[2:3], v[66:67] op_sel_hi:[1,0]
	v_cvt_pk_bf16_f32 v0, v0, v1
	v_cvt_pk_bf16_f32 v1, v2, v3
	v_pk_add_f32 v[2:3], v[12:13], v[64:65] op_sel_hi:[1,0] neg_lo:[0,1] neg_hi:[0,1]
	v_pk_add_f32 v[4:5], v[14:15], v[64:65] op_sel_hi:[1,0] neg_lo:[0,1] neg_hi:[0,1]
	v_pk_mul_f32 v[2:3], v[2:3], v[66:67] op_sel_hi:[1,0]
	v_pk_mul_f32 v[4:5], v[4:5], v[66:67] op_sel_hi:[1,0]
	v_cvt_pk_bf16_f32 v2, v2, v3
	v_cvt_pk_bf16_f32 v3, v4, v5
	ds_write2_b64 v6, v[0:1], v[2:3] offset0:4 offset1:6
	v_pk_add_f32 v[0:1], v[16:17], v[64:65] op_sel_hi:[1,0] neg_lo:[0,1] neg_hi:[0,1]
	v_pk_add_f32 v[2:3], v[18:19], v[64:65] op_sel_hi:[1,0] neg_lo:[0,1] neg_hi:[0,1]
	v_pk_mul_f32 v[0:1], v[0:1], v[66:67] op_sel_hi:[1,0]
	v_pk_mul_f32 v[2:3], v[2:3], v[66:67] op_sel_hi:[1,0]
	v_cvt_pk_bf16_f32 v0, v0, v1
	v_cvt_pk_bf16_f32 v1, v2, v3
	v_pk_add_f32 v[2:3], v[20:21], v[64:65] op_sel_hi:[1,0] neg_lo:[0,1] neg_hi:[0,1]
	v_pk_add_f32 v[4:5], v[22:23], v[64:65] op_sel_hi:[1,0] neg_lo:[0,1] neg_hi:[0,1]
	v_pk_mul_f32 v[2:3], v[2:3], v[66:67] op_sel_hi:[1,0]
	v_pk_mul_f32 v[4:5], v[4:5], v[66:67] op_sel_hi:[1,0]
	v_cvt_pk_bf16_f32 v2, v2, v3
	v_cvt_pk_bf16_f32 v3, v4, v5
	ds_write2_b64 v6, v[0:1], v[2:3] offset0:8 offset1:10
	v_pk_add_f32 v[0:1], v[24:25], v[64:65] op_sel_hi:[1,0] neg_lo:[0,1] neg_hi:[0,1]
	v_pk_add_f32 v[2:3], v[26:27], v[64:65] op_sel_hi:[1,0] neg_lo:[0,1] neg_hi:[0,1]
; #define LAS __attribute__((address_space(3)))
; __device__ __forceinline__ unsigned pk2(float lo, float hi) { return cvt_pk_bf16(lo, hi); }
; __device__ __forceinline__ float fsigmoid(float x) { return __builtin_amdgcn_rcpf(1.0f + fexp(-x)); }
; __device__ __forceinline__ void phase_ret_out(const Frame& F, const Args& a, int l) {
;     ...
;         for (int j = 0; j < 8; ++j) {
;             const int idx = lane + 64 * j, q = idx >> 4, cv = idx & 15, col = h * 256 + 128 * dj + 8 * cv;
;             const v4u ov = *(const LAS v4u*)(stg + q * PLD + cv * 16);
;             const size_t tok = tok0 + 32 * qi + q;
;             const v4u gv = *(const v4u*)(RG + tok * 1024 + col);
;             const f32x4 r0 = *(const f32x4*)(rn + col), r1 = *(const f32x4*)(rn + col + 4);
;             const float rr[8] = {r0.x, r0.y, r0.z, r0.w, r1.x, r1.y, r1.z, r1.w};
;             v4u wv;
; #pragma unroll
;             for (int q2 = 0; q2 < 4; ++q2) { const float ga = bf_lo(gv[q2]), gb = bf_hi(gv[q2]);
;                 wv[q2] = pk2(ga * fsigmoid(ga) * bf_lo(ov[q2]) * rr[2 * q2], gb * fsigmoid(gb) * bf_hi(ov[q2]) * rr[2 * q2 + 1]); }
;             *(v4u*)(YB + tok * 1024 + col) = wv;
;         }
	v_pk_mul_f32 v[0:1], v[0:1], v[66:67] op_sel_hi:[1,0]
	v_pk_mul_f32 v[2:3], v[2:3], v[66:67] op_sel_hi:[1,0]
	v_cvt_pk_bf16_f32 v0, v0, v1
	v_cvt_pk_bf16_f32 v1, v2, v3
	v_pk_add_f32 v[2:3], v[28:29], v[64:65] op_sel_hi:[1,0] neg_lo:[0,1] neg_hi:[0,1]
	v_pk_add_f32 v[4:5], v[30:31], v[64:65] op_sel_hi:[1,0] neg_lo:[0,1] neg_hi:[0,1]
	v_pk_mul_f32 v[2:3], v[2:3], v[66:67] op_sel_hi:[1,0]
	v_pk_mul_f32 v[4:5], v[4:5], v[66:67] op_sel_hi:[1,0]
	v_cvt_pk_bf16_f32 v2, v2, v3
	v_cvt_pk_bf16_f32 v3, v4, v5
	ds_write2_b64 v6, v[0:1], v[2:3] offset0:12 offset1:14
	v_pk_add_f32 v[0:1], v[32:33], v[64:65] op_sel_hi:[1,0] neg_lo:[0,1] neg_hi:[0,1]
	v_pk_add_f32 v[2:3], v[34:35], v[64:65] op_sel_hi:[1,0] neg_lo:[0,1] neg_hi:[0,1]
	v_pk_mul_f32 v[0:1], v[0:1], v[66:67] op_sel_hi:[1,0]
	v_pk_mul_f32 v[2:3], v[2:3], v[66:67] op_sel_hi:[1,0]
	v_cvt_pk_bf16_f32 v0, v0, v1
	v_cvt_pk_bf16_f32 v1, v2, v3
	v_pk_add_f32 v[2:3], v[36:37], v[64:65] op_sel_hi:[1,0] neg_lo:[0,1] neg_hi:[0,1]
	v_pk_add_f32 v[4:5], v[38:39], v[64:65] op_sel_hi:[1,0] neg_lo:[0,1] neg_hi:[0,1]
	v_pk_mul_f32 v[2:3], v[2:3], v[66:67] op_sel_hi:[1,0]
	v_pk_mul_f32 v[4:5], v[4:5], v[66:67] op_sel_hi:[1,0]
	v_cvt_pk_bf16_f32 v2, v2, v3
	v_cvt_pk_bf16_f32 v3, v4, v5
	ds_write2_b64 v6, v[0:1], v[2:3] offset0:16 offset1:18
	v_pk_add_f32 v[0:1], v[40:41], v[64:65] op_sel_hi:[1,0] neg_lo:[0,1] neg_hi:[0,1]
	v_pk_add_f32 v[2:3], v[42:43], v[64:65] op_sel_hi:[1,0] neg_lo:[0,1] neg_hi:[0,1]
	v_pk_mul_f32 v[0:1], v[0:1], v[66:67] op_sel_hi:[1,0]
	v_pk_mul_f32 v[2:3], v[2:3], v[66:67] op_sel_hi:[1,0]
	v_cvt_pk_bf16_f32 v0, v0, v1
	v_cvt_pk_bf16_f32 v1, v2, v3
	v_pk_add_f32 v[2:3], v[44:45], v[64:65] op_sel_hi:[1,0] neg_lo:[0,1] neg_hi:[0,1]
	v_pk_add_f32 v[4:5], v[46:47], v[64:65] op_sel_hi:[1,0] neg_lo:[0,1] neg_hi:[0,1]
	v_pk_mul_f32 v[2:3], v[2:3], v[66:67] op_sel_hi:[1,0]
	v_pk_mul_f32 v[4:5], v[4:5], v[66:67] op_sel_hi:[1,0]
	v_cvt_pk_bf16_f32 v2, v2, v3
	v_cvt_pk_bf16_f32 v3, v4, v5
	ds_write2_b64 v6, v[0:1], v[2:3] offset0:20 offset1:22
	v_pk_add_f32 v[0:1], v[48:49], v[64:65] op_sel_hi:[1,0] neg_lo:[0,1] neg_hi:[0,1]
	v_pk_add_f32 v[2:3], v[50:51], v[64:65] op_sel_hi:[1,0] neg_lo:[0,1] neg_hi:[0,1]
	v_pk_mul_f32 v[0:1], v[0:1], v[66:67] op_sel_hi:[1,0]
	v_pk_mul_f32 v[2:3], v[2:3], v[66:67] op_sel_hi:[1,0]
	v_cvt_pk_bf16_f32 v0, v0, v1
	v_cvt_pk_bf16_f32 v1, v2, v3
	v_pk_add_f32 v[2:3], v[52:53], v[64:65] op_sel_hi:[1,0] neg_lo:[0,1] neg_hi:[0,1]
	v_pk_add_f32 v[4:5], v[54:55], v[64:65] op_sel_hi:[1,0] neg_lo:[0,1] neg_hi:[0,1]
	v_pk_mul_f32 v[2:3], v[2:3], v[66:67] op_sel_hi:[1,0]
	v_pk_mul_f32 v[4:5], v[4:5], v[66:67] op_sel_hi:[1,0]
	v_cvt_pk_bf16_f32 v2, v2, v3
	v_cvt_pk_bf16_f32 v3, v4, v5
	ds_write2_b64 v6, v[0:1], v[2:3] offset0:24 offset1:26
	v_pk_add_f32 v[0:1], v[56:57], v[64:65] op_sel_hi:[1,0] neg_lo:[0,1] neg_hi:[0,1]
	v_pk_add_f32 v[2:3], v[58:59], v[64:65] op_sel_hi:[1,0] neg_lo:[0,1] neg_hi:[0,1]
	v_pk_mul_f32 v[0:1], v[0:1], v[66:67] op_sel_hi:[1,0]
	v_pk_mul_f32 v[2:3], v[2:3], v[66:67] op_sel_hi:[1,0]
	v_cvt_pk_bf16_f32 v0, v0, v1
	v_cvt_pk_bf16_f32 v1, v2, v3
	v_pk_add_f32 v[2:3], v[60:61], v[64:65] op_sel_hi:[1,0] neg_lo:[0,1] neg_hi:[0,1]
	v_pk_add_f32 v[4:5], v[62:63], v[64:65] op_sel_hi:[1,0] neg_lo:[0,1] neg_hi:[0,1]
	v_pk_mul_f32 v[2:3], v[2:3], v[66:67] op_sel_hi:[1,0]
	v_pk_mul_f32 v[4:5], v[4:5], v[66:67] op_sel_hi:[1,0]
	v_cvt_pk_bf16_f32 v2, v2, v3
	v_cvt_pk_bf16_f32 v3, v4, v5
	ds_write2_b64 v6, v[0:1], v[2:3] offset0:28 offset1:30
	v_lshl_add_u32 v0, s23, 8, v117
	v_ashrrev_i32_e32 v1, 31, v0
	v_lshlrev_b64 v[2:3], 1, v[0:1]
	v_mov_b32_e32 v5, s25
	v_or_b32_e32 v4, s24, v110
	s_waitcnt lgkmcnt(0)
	v_lshl_add_u64 v[8:9], s[12:13], 0, v[2:3]
	v_lshlrev_b64 v[26:27], 11, v[4:5]
	v_lshl_add_u64 v[4:5], v[8:9], 0, v[26:27]
	s_nop 1
	s_waitcnt vmcnt(7)
	v_lshl_add_u64 v[6:7], v[0:1], 2, s[18:19]
	ds_read_b128 v[22:25], v129 offset:40960
	s_nop 0
	v_lshlrev_b32_e32 v0, 16, v132
	v_and_b32_e32 v1, 0xffff0000, v132
	v_mul_f32_e32 v4, 0xbfb8aa3b, v0
	v_exp_f32_e32 v4, v4
	v_mul_f32_e32 v5, 0xbfb8aa3b, v1
	v_exp_f32_e32 v5, v5
	v_lshlrev_b32_e32 v30, 16, v133
	v_add_f32_e32 v4, 1.0, v4
	v_rcp_f32_e32 v28, v4
	v_add_f32_e32 v4, 1.0, v5
	v_and_b32_e32 v31, 0xffff0000, v133
	v_mul_f32_e32 v11, 0xbfb8aa3b, v30
	v_rcp_f32_e32 v29, v4
	v_exp_f32_e32 v32, v11
	v_mul_f32_e32 v11, 0xbfb8aa3b, v31
	v_exp_f32_e32 v33, v11
	v_lshl_add_u64 v[4:5], s[14:15], 0, v[2:3]
	v_pk_mul_f32 v[28:29], v[28:29], v[0:1]
	ds_read_b128 v[0:3], v129 offset:42048
	s_waitcnt lgkmcnt(1)
	v_lshlrev_b32_e32 v10, 16, v22
	v_and_b32_e32 v11, 0xffff0000, v22
	v_add_f32_e32 v22, 1.0, v32
	v_rcp_f32_e32 v32, v22
	v_add_f32_e32 v22, 1.0, v33
	v_rcp_f32_e32 v33, v22
	v_pk_mul_f32 v[10:11], v[28:29], v[10:11]
	v_lshlrev_b32_e32 v22, 16, v23
	s_nop 0
	v_pk_mul_f32 v[10:11], v[164:165], v[10:11]
	v_pk_mul_f32 v[14:15], v[32:33], v[30:31]
	v_and_b32_e32 v23, 0xffff0000, v23
	v_lshlrev_b32_e32 v28, 16, v134
	v_pk_mul_f32 v[14:15], v[14:15], v[22:23]
	v_cvt_pk_bf16_f32 v10, v10, v11
	v_and_b32_e32 v29, 0xffff0000, v134
	v_mul_f32_e32 v11, 0xbfb8aa3b, v28
	v_pk_mul_f32 v[14:15], v[166:167], v[14:15]
	v_lshlrev_b32_e32 v16, 16, v135
	v_exp_f32_e32 v11, v11
	v_mul_f32_e32 v12, 0xbfb8aa3b, v29
	v_and_b32_e32 v17, 0xffff0000, v135
	v_mul_f32_e32 v13, 0xbfb8aa3b, v16
	v_exp_f32_e32 v12, v12
	v_exp_f32_e32 v22, v13
	v_mul_f32_e32 v13, 0xbfb8aa3b, v17
	v_exp_f32_e32 v23, v13
	v_add_f32_e32 v11, 1.0, v11
	v_rcp_f32_e32 v30, v11
	v_add_f32_e32 v11, 1.0, v12
	v_rcp_f32_e32 v31, v11
	v_add_f32_e32 v22, 1.0, v22
	v_add_f32_e32 v23, 1.0, v23
	v_rcp_f32_e32 v22, v22
	v_rcp_f32_e32 v23, v23
	v_cvt_pk_bf16_f32 v11, v14, v15
	v_pk_mul_f32 v[14:15], v[30:31], v[28:29]
	v_lshlrev_b32_e32 v12, 16, v24
	v_and_b32_e32 v13, 0xffff0000, v24
	v_pk_mul_f32 v[12:13], v[14:15], v[12:13]
	v_pk_mul_f32 v[14:15], v[22:23], v[16:17]
	v_lshlrev_b32_e32 v16, 16, v25
	v_and_b32_e32 v17, 0xffff0000, v25
	v_pk_mul_f32 v[14:15], v[14:15], v[16:17]
	s_nop 0
	v_pk_mul_f32 v[12:13], v[168:169], v[12:13]
	v_pk_mul_f32 v[14:15], v[170:171], v[14:15]
	v_cvt_pk_bf16_f32 v12, v12, v13
	v_cvt_pk_bf16_f32 v13, v14, v15
	v_lshl_add_u64 v[14:15], v[4:5], 0, v[26:27]
	global_store_dwordx4 v[14:15], v[10:13], off
	s_nop 1
	v_mov_b32_e32 v11, s25
	v_or_b32_e32 v10, s24, v112
	v_lshlrev_b64 v[22:23], 11, v[10:11]
	v_lshl_add_u64 v[10:11], v[8:9], 0, v[22:23]
	s_nop 1
	s_waitcnt vmcnt(7)
; #define LAS __attribute__((address_space(3)))
; __device__ __forceinline__ unsigned pk2(float lo, float hi) { return cvt_pk_bf16(lo, hi); }
; __device__ __forceinline__ float fsigmoid(float x) { return __builtin_amdgcn_rcpf(1.0f + fexp(-x)); }
; __device__ __forceinline__ void phase_ret_out(const Frame& F, const Args& a, int l) {
;     ...
;         for (int j = 0; j < 8; ++j) {
;             const int idx = lane + 64 * j, q = idx >> 4, cv = idx & 15, col = h * 256 + 128 * dj + 8 * cv;
;             const v4u ov = *(const LAS v4u*)(stg + q * PLD + cv * 16);
;             const size_t tok = tok0 + 32 * qi + q;
;             const v4u gv = *(const v4u*)(RG + tok * 1024 + col);
;             const f32x4 r0 = *(const f32x4*)(rn + col), r1 = *(const f32x4*)(rn + col + 4);
;             const float rr[8] = {r0.x, r0.y, r0.z, r0.w, r1.x, r1.y, r1.z, r1.w};
;             v4u wv;
; #pragma unroll
;             for (int q2 = 0; q2 < 4; ++q2) { const float ga = bf_lo(gv[q2]), gb = bf_hi(gv[q2]);
;                 wv[q2] = pk2(ga * fsigmoid(ga) * bf_lo(ov[q2]) * rr[2 * q2], gb * fsigmoid(gb) * bf_hi(ov[q2]) * rr[2 * q2 + 1]); }
;             *(v4u*)(YB + tok * 1024 + col) = wv;
;         }
	s_nop 0
	s_nop 0
	v_lshlrev_b32_e32 v24, 16, v136
	v_and_b32_e32 v25, 0xffff0000, v136
	v_mul_f32_e32 v10, 0xbfb8aa3b, v24
	v_exp_f32_e32 v10, v10
	v_mul_f32_e32 v26, 0xbfb8aa3b, v25
	v_exp_f32_e32 v27, v26
	v_add_f32_e32 v10, 1.0, v10
	v_rcp_f32_e32 v26, v10
	v_add_f32_e32 v10, 1.0, v27
	v_rcp_f32_e32 v27, v10
	s_waitcnt lgkmcnt(0)
	v_lshlrev_b32_e32 v10, 16, v0
	v_pk_mul_f32 v[24:25], v[26:27], v[24:25]
	v_lshlrev_b32_e32 v26, 16, v137
	v_and_b32_e32 v27, 0xffff0000, v137
	v_mul_f32_e32 v11, 0xbfb8aa3b, v26
	v_exp_f32_e32 v28, v11
	v_mul_f32_e32 v11, 0xbfb8aa3b, v27
	v_exp_f32_e32 v29, v11
	v_and_b32_e32 v11, 0xffff0000, v0
	v_add_f32_e32 v0, 1.0, v28
	v_rcp_f32_e32 v28, v0
	v_add_f32_e32 v0, 1.0, v29
	v_rcp_f32_e32 v29, v0
	v_pk_mul_f32 v[10:11], v[24:25], v[10:11]
	v_lshlrev_b32_e32 v24, 16, v138
	v_and_b32_e32 v25, 0xffff0000, v138
	s_nop 0
	v_pk_mul_f32 v[10:11], v[164:165], v[10:11]
	v_mul_f32_e32 v12, 0xbfb8aa3b, v24
	v_mul_f32_e32 v15, 0xbfb8aa3b, v25
	v_cvt_pk_bf16_f32 v0, v10, v11
	v_pk_mul_f32 v[10:11], v[28:29], v[26:27]
	v_lshlrev_b32_e32 v14, 16, v1
	v_exp_f32_e32 v12, v12
	v_exp_f32_e32 v27, v15
	v_and_b32_e32 v15, 0xffff0000, v1
	v_pk_mul_f32 v[10:11], v[10:11], v[14:15]
	v_lshlrev_b32_e32 v14, 16, v139
	v_and_b32_e32 v15, 0xffff0000, v139
	v_mul_f32_e32 v13, 0xbfb8aa3b, v14
	v_pk_mul_f32 v[10:11], v[166:167], v[10:11]
	v_exp_f32_e32 v16, v13
	v_mul_f32_e32 v13, 0xbfb8aa3b, v15
	v_add_f32_e32 v1, 1.0, v12
	v_exp_f32_e32 v17, v13
	v_rcp_f32_e32 v26, v1
	v_add_f32_e32 v1, 1.0, v27
	v_rcp_f32_e32 v27, v1
	v_lshlrev_b32_e32 v12, 16, v2
	v_and_b32_e32 v13, 0xffff0000, v2
	v_add_f32_e32 v2, 1.0, v16
	v_rcp_f32_e32 v16, v2
	v_add_f32_e32 v2, 1.0, v17
	v_rcp_f32_e32 v17, v2
	v_cvt_pk_bf16_f32 v1, v10, v11
	v_pk_mul_f32 v[10:11], v[26:27], v[24:25]
	s_nop 0
	v_pk_mul_f32 v[10:11], v[10:11], v[12:13]
	v_lshlrev_b32_e32 v12, 16, v3
	s_nop 0
	v_pk_mul_f32 v[10:11], v[168:169], v[10:11]
	v_and_b32_e32 v13, 0xffff0000, v3
	v_cvt_pk_bf16_f32 v2, v10, v11
	v_pk_mul_f32 v[10:11], v[16:17], v[14:15]
	s_nop 0
	v_pk_mul_f32 v[10:11], v[10:11], v[12:13]
	s_nop 0
	v_pk_mul_f32 v[10:11], v[170:171], v[10:11]
	s_nop 0
	v_cvt_pk_bf16_f32 v3, v10, v11
	v_lshl_add_u64 v[10:11], v[4:5], 0, v[22:23]
	global_store_dwordx4 v[10:11], v[0:3], off
	s_nop 1
	v_mov_b32_e32 v1, s25
	v_or_b32_e32 v0, s24, v114
	v_lshlrev_b64 v[26:27], 11, v[0:1]
	v_lshl_add_u64 v[0:1], v[8:9], 0, v[26:27]
	s_nop 1
	s_waitcnt vmcnt(7)
	ds_read_b128 v[22:25], v129 offset:43136
	s_nop 0
	v_lshlrev_b32_e32 v28, 16, v140
	v_and_b32_e32 v29, 0xffff0000, v140
	v_mul_f32_e32 v0, 0xbfb8aa3b, v28
	v_mul_f32_e32 v1, 0xbfb8aa3b, v29
	v_exp_f32_e32 v30, v0
	v_exp_f32_e32 v31, v1
	v_lshlrev_b32_e32 v32, 16, v141
	v_and_b32_e32 v33, 0xffff0000, v141
	v_add_f32_e32 v30, 1.0, v30
	v_add_f32_e32 v31, 1.0, v31
	v_rcp_f32_e32 v30, v30
	v_rcp_f32_e32 v31, v31
	v_mul_f32_e32 v11, 0xbfb8aa3b, v32
	ds_read_b128 v[0:3], v129 offset:44224
	s_waitcnt lgkmcnt(1)
	v_lshlrev_b32_e32 v10, 16, v22
	v_pk_mul_f32 v[28:29], v[30:31], v[28:29]
	v_exp_f32_e32 v30, v11
	v_mul_f32_e32 v11, 0xbfb8aa3b, v33
	v_exp_f32_e32 v31, v11
	v_and_b32_e32 v11, 0xffff0000, v22
	v_add_f32_e32 v22, 1.0, v30
	v_rcp_f32_e32 v30, v22
	v_add_f32_e32 v22, 1.0, v31
	v_rcp_f32_e32 v31, v22
	v_pk_mul_f32 v[10:11], v[28:29], v[10:11]
	v_lshlrev_b32_e32 v22, 16, v23
	s_nop 0
	v_pk_mul_f32 v[10:11], v[164:165], v[10:11]
	v_pk_mul_f32 v[14:15], v[30:31], v[32:33]
	v_and_b32_e32 v23, 0xffff0000, v23
	v_lshlrev_b32_e32 v28, 16, v142
	v_pk_mul_f32 v[14:15], v[14:15], v[22:23]
	v_cvt_pk_bf16_f32 v10, v10, v11
	v_and_b32_e32 v29, 0xffff0000, v142
	v_mul_f32_e32 v11, 0xbfb8aa3b, v28
	v_pk_mul_f32 v[14:15], v[166:167], v[14:15]
	v_lshlrev_b32_e32 v16, 16, v143
	v_exp_f32_e32 v11, v11
	v_mul_f32_e32 v12, 0xbfb8aa3b, v29
	v_and_b32_e32 v17, 0xffff0000, v143
	v_mul_f32_e32 v13, 0xbfb8aa3b, v16
	v_exp_f32_e32 v12, v12
	v_exp_f32_e32 v22, v13
	v_mul_f32_e32 v13, 0xbfb8aa3b, v17
	v_exp_f32_e32 v23, v13
	v_add_f32_e32 v11, 1.0, v11
	v_rcp_f32_e32 v30, v11
	v_add_f32_e32 v11, 1.0, v12
	v_rcp_f32_e32 v31, v11
	v_add_f32_e32 v22, 1.0, v22
	v_add_f32_e32 v23, 1.0, v23
	v_rcp_f32_e32 v22, v22
	v_rcp_f32_e32 v23, v23
	v_cvt_pk_bf16_f32 v11, v14, v15
	v_pk_mul_f32 v[14:15], v[30:31], v[28:29]
	v_lshlrev_b32_e32 v12, 16, v24
	v_and_b32_e32 v13, 0xffff0000, v24
	v_pk_mul_f32 v[12:13], v[14:15], v[12:13]
	v_pk_mul_f32 v[14:15], v[22:23], v[16:17]
	v_lshlrev_b32_e32 v16, 16, v25
	v_and_b32_e32 v17, 0xffff0000, v25
	v_pk_mul_f32 v[14:15], v[14:15], v[16:17]
	s_nop 0
	v_pk_mul_f32 v[12:13], v[168:169], v[12:13]
	v_pk_mul_f32 v[14:15], v[170:171], v[14:15]
	v_cvt_pk_bf16_f32 v12, v12, v13
	v_cvt_pk_bf16_f32 v13, v14, v15
	v_lshl_add_u64 v[14:15], v[4:5], 0, v[26:27]
	global_store_dwordx4 v[14:15], v[10:13], off
	s_waitcnt lgkmcnt(0)
	v_lshlrev_b32_e32 v24, 16, v0
	v_and_b32_e32 v25, 0xffff0000, v0
	v_mov_b32_e32 v11, s25
	v_or_b32_e32 v10, s24, v116
	v_lshlrev_b64 v[22:23], 11, v[10:11]
	v_lshl_add_u64 v[10:11], v[8:9], 0, v[22:23]
	s_nop 1
	s_waitcnt vmcnt(7)
; #define LAS __attribute__((address_space(3)))
; __device__ __forceinline__ unsigned pk2(float lo, float hi) { return cvt_pk_bf16(lo, hi); }
; __device__ __forceinline__ float fsigmoid(float x) { return __builtin_amdgcn_rcpf(1.0f + fexp(-x)); }
; __device__ __forceinline__ void phase_ret_out(const Frame& F, const Args& a, int l) {
;     ...
;         for (int j = 0; j < 8; ++j) {
;             const int idx = lane + 64 * j, q = idx >> 4, cv = idx & 15, col = h * 256 + 128 * dj + 8 * cv;
;             const v4u ov = *(const LAS v4u*)(stg + q * PLD + cv * 16);
;             const size_t tok = tok0 + 32 * qi + q;
;             const v4u gv = *(const v4u*)(RG + tok * 1024 + col);
;             const f32x4 r0 = *(const f32x4*)(rn + col), r1 = *(const f32x4*)(rn + col + 4);
;             const float rr[8] = {r0.x, r0.y, r0.z, r0.w, r1.x, r1.y, r1.z, r1.w};
;             v4u wv;
; #pragma unroll
;             for (int q2 = 0; q2 < 4; ++q2) { const float ga = bf_lo(gv[q2]), gb = bf_hi(gv[q2]);
;                 wv[q2] = pk2(ga * fsigmoid(ga) * bf_lo(ov[q2]) * rr[2 * q2], gb * fsigmoid(gb) * bf_hi(ov[q2]) * rr[2 * q2 + 1]); }
;             *(v4u*)(YB + tok * 1024 + col) = wv;
;         }
	s_nop 0
	v_lshlrev_b32_e32 v0, 16, v1
	v_and_b32_e32 v1, 0xffff0000, v1
	s_nop 0
	v_lshlrev_b32_e32 v26, 16, v144
	v_and_b32_e32 v27, 0xffff0000, v144
	v_lshlrev_b32_e32 v10, 16, v145
	v_and_b32_e32 v11, 0xffff0000, v145
	v_lshlrev_b32_e32 v28, 16, v146
	v_and_b32_e32 v29, 0xffff0000, v146
	v_mul_f32_e32 v12, 0xbfb8aa3b, v26
	v_mul_f32_e32 v30, 0xbfb8aa3b, v27
	v_mul_f32_e32 v31, 0xbfb8aa3b, v10
	v_mul_f32_e32 v32, 0xbfb8aa3b, v11
	v_mul_f32_e32 v33, 0xbfb8aa3b, v28
	v_exp_f32_e32 v12, v12
	v_exp_f32_e32 v30, v30
	v_exp_f32_e32 v31, v31
	v_exp_f32_e32 v32, v32
	v_exp_f32_e32 v33, v33
	v_add_f32_e32 v12, 1.0, v12
	v_add_f32_e32 v35, 1.0, v30
	v_add_f32_e32 v36, 1.0, v31
	v_add_f32_e32 v37, 1.0, v32
	v_add_f32_e32 v38, 1.0, v33
	v_rcp_f32_e32 v30, v12
	v_rcp_f32_e32 v31, v35
	v_rcp_f32_e32 v32, v36
	v_rcp_f32_e32 v33, v37
	v_mul_f32_e32 v34, 0xbfb8aa3b, v29
	v_pk_mul_f32 v[26:27], v[30:31], v[26:27]
	v_exp_f32_e32 v34, v34
	v_pk_mul_f32 v[10:11], v[32:33], v[10:11]
	v_pk_mul_f32 v[24:25], v[26:27], v[24:25]
	v_pk_mul_f32 v[0:1], v[10:11], v[0:1]
	s_nop 0
	v_pk_mul_f32 v[10:11], v[164:165], v[24:25]
	v_pk_mul_f32 v[14:15], v[166:167], v[0:1]
	v_add_f32_e32 v39, 1.0, v34
	v_cvt_pk_bf16_f32 v1, v14, v15
	v_lshlrev_b32_e32 v14, 16, v147
	v_and_b32_e32 v15, 0xffff0000, v147
	v_mul_f32_e32 v13, 0xbfb8aa3b, v14
	v_exp_f32_e32 v16, v13
	v_mul_f32_e32 v13, 0xbfb8aa3b, v15
	v_exp_f32_e32 v17, v13
	v_rcp_f32_e32 v34, v38
	v_rcp_f32_e32 v35, v39
	v_lshlrev_b32_e32 v12, 16, v2
	v_and_b32_e32 v13, 0xffff0000, v2
	v_add_f32_e32 v2, 1.0, v16
	v_rcp_f32_e32 v16, v2
	v_add_f32_e32 v2, 1.0, v17
	v_rcp_f32_e32 v17, v2
	v_cvt_pk_bf16_f32 v0, v10, v11
	v_pk_mul_f32 v[10:11], v[34:35], v[28:29]
	s_nop 0
	v_pk_mul_f32 v[10:11], v[10:11], v[12:13]
	v_lshlrev_b32_e32 v12, 16, v3
	s_nop 0
	v_pk_mul_f32 v[10:11], v[168:169], v[10:11]
	v_and_b32_e32 v13, 0xffff0000, v3
	v_cvt_pk_bf16_f32 v2, v10, v11
	v_pk_mul_f32 v[10:11], v[16:17], v[14:15]
	s_nop 0
	v_pk_mul_f32 v[10:11], v[10:11], v[12:13]
	s_nop 0
	v_pk_mul_f32 v[10:11], v[170:171], v[10:11]
	s_nop 0
	v_cvt_pk_bf16_f32 v3, v10, v11
	v_lshl_add_u64 v[10:11], v[4:5], 0, v[22:23]
	global_store_dwordx4 v[10:11], v[0:3], off
	s_nop 1
	v_mov_b32_e32 v1, s25
	v_or_b32_e32 v0, s24, v118
	v_lshlrev_b64 v[26:27], 11, v[0:1]
	v_lshl_add_u64 v[0:1], v[8:9], 0, v[26:27]
	s_nop 1
	s_waitcnt vmcnt(7)
	ds_read_b128 v[22:25], v129 offset:45312
	ds_read_b128 v[0:3], v129 offset:46400
	s_waitcnt lgkmcnt(1)
	v_lshlrev_b32_e32 v28, 16, v22
	v_and_b32_e32 v29, 0xffff0000, v22
	v_lshlrev_b32_e32 v22, 16, v23
	v_and_b32_e32 v23, 0xffff0000, v23
	v_lshlrev_b32_e32 v30, 16, v24
	v_and_b32_e32 v31, 0xffff0000, v24
	v_lshlrev_b32_e32 v24, 16, v25
	v_and_b32_e32 v25, 0xffff0000, v25
	s_nop 0
	v_lshlrev_b32_e32 v32, 16, v148
	v_and_b32_e32 v33, 0xffff0000, v148
	v_lshlrev_b32_e32 v10, 16, v149
	v_and_b32_e32 v11, 0xffff0000, v149
	v_lshlrev_b32_e32 v34, 16, v150
	v_and_b32_e32 v35, 0xffff0000, v150
	v_lshlrev_b32_e32 v12, 16, v151
	v_and_b32_e32 v13, 0xffff0000, v151
	v_mul_f32_e32 v36, 0xbfb8aa3b, v32
	v_mul_f32_e32 v37, 0xbfb8aa3b, v33
	v_mul_f32_e32 v38, 0xbfb8aa3b, v10
	v_mul_f32_e32 v39, 0xbfb8aa3b, v11
	v_mul_f32_e32 v40, 0xbfb8aa3b, v34
	v_mul_f32_e32 v41, 0xbfb8aa3b, v35
	v_mul_f32_e32 v42, 0xbfb8aa3b, v12
	v_mul_f32_e32 v43, 0xbfb8aa3b, v13
	v_exp_f32_e32 v36, v36
	v_exp_f32_e32 v37, v37
	v_exp_f32_e32 v38, v38
	v_exp_f32_e32 v39, v39
	v_exp_f32_e32 v40, v40
	v_exp_f32_e32 v41, v41
	v_exp_f32_e32 v42, v42
	v_exp_f32_e32 v43, v43
	v_add_f32_e32 v36, 1.0, v36
	v_add_f32_e32 v37, 1.0, v37
	v_add_f32_e32 v38, 1.0, v38
	v_add_f32_e32 v39, 1.0, v39
	v_add_f32_e32 v40, 1.0, v40
	v_add_f32_e32 v41, 1.0, v41
	v_add_f32_e32 v42, 1.0, v42
	v_add_f32_e32 v43, 1.0, v43
	v_rcp_f32_e32 v36, v36
	v_rcp_f32_e32 v37, v37
	v_rcp_f32_e32 v38, v38
	v_rcp_f32_e32 v39, v39
	v_rcp_f32_e32 v40, v40
	v_rcp_f32_e32 v41, v41
	v_rcp_f32_e32 v42, v42
	v_rcp_f32_e32 v43, v43
	v_pk_mul_f32 v[32:33], v[36:37], v[32:33]
	v_pk_mul_f32 v[10:11], v[38:39], v[10:11]
	v_pk_mul_f32 v[34:35], v[40:41], v[34:35]
	v_pk_mul_f32 v[12:13], v[42:43], v[12:13]
	v_pk_mul_f32 v[28:29], v[32:33], v[28:29]
	v_pk_mul_f32 v[10:11], v[10:11], v[22:23]
	v_pk_mul_f32 v[22:23], v[34:35], v[30:31]
	v_pk_mul_f32 v[24:25], v[12:13], v[24:25]
	s_nop 0
	v_pk_mul_f32 v[12:13], v[164:165], v[28:29]
	v_pk_mul_f32 v[14:15], v[166:167], v[10:11]
	s_nop 0
	v_pk_mul_f32 v[16:17], v[168:169], v[22:23]
	v_cvt_pk_bf16_f32 v11, v14, v15
	v_pk_mul_f32 v[14:15], v[170:171], v[24:25]
	v_cvt_pk_bf16_f32 v10, v12, v13
	v_cvt_pk_bf16_f32 v12, v16, v17
	v_cvt_pk_bf16_f32 v13, v14, v15
	v_lshl_add_u64 v[14:15], v[4:5], 0, v[26:27]
	global_store_dwordx4 v[14:15], v[10:13], off
	s_waitcnt lgkmcnt(0)
	v_lshlrev_b32_e32 v28, 16, v0
	v_and_b32_e32 v29, 0xffff0000, v0
	v_mov_b32_e32 v11, s25
	v_or_b32_e32 v10, s24, v120
	v_lshlrev_b64 v[22:23], 11, v[10:11]
	v_lshl_add_u64 v[10:11], v[8:9], 0, v[22:23]
	s_nop 1
	s_waitcnt vmcnt(7)
; #define LAS __attribute__((address_space(3)))
; __device__ __forceinline__ unsigned pk2(float lo, float hi) { return cvt_pk_bf16(lo, hi); }
; __device__ __forceinline__ float fsigmoid(float x) { return __builtin_amdgcn_rcpf(1.0f + fexp(-x)); }
; __device__ __forceinline__ void phase_ret_out(const Frame& F, const Args& a, int l) {
;     ...
;         for (int j = 0; j < 8; ++j) {
;             const int idx = lane + 64 * j, q = idx >> 4, cv = idx & 15, col = h * 256 + 128 * dj + 8 * cv;
;             const v4u ov = *(const LAS v4u*)(stg + q * PLD + cv * 16);
;             const size_t tok = tok0 + 32 * qi + q;
;             const v4u gv = *(const v4u*)(RG + tok * 1024 + col);
;             const f32x4 r0 = *(const f32x4*)(rn + col), r1 = *(const f32x4*)(rn + col + 4);
;             const float rr[8] = {r0.x, r0.y, r0.z, r0.w, r1.x, r1.y, r1.z, r1.w};
;             v4u wv;
; #pragma unroll
;             for (int q2 = 0; q2 < 4; ++q2) { const float ga = bf_lo(gv[q2]), gb = bf_hi(gv[q2]);
;                 wv[q2] = pk2(ga * fsigmoid(ga) * bf_lo(ov[q2]) * rr[2 * q2], gb * fsigmoid(gb) * bf_hi(ov[q2]) * rr[2 * q2 + 1]); }
;             *(v4u*)(YB + tok * 1024 + col) = wv;
;         }
	s_nop 0
	v_lshlrev_b32_e32 v0, 16, v1
	v_and_b32_e32 v1, 0xffff0000, v1
	v_lshlrev_b32_e32 v30, 16, v2
	v_and_b32_e32 v31, 0xffff0000, v2
	v_lshlrev_b32_e32 v2, 16, v3
	v_and_b32_e32 v3, 0xffff0000, v3
	v_mov_b32_e32 v25, s25
	v_or_b32_e32 v24, s24, v122
	v_lshlrev_b64 v[24:25], 11, v[24:25]
	v_lshl_add_u64 v[22:23], v[4:5], 0, v[22:23]
	v_lshl_add_u64 v[26:27], v[8:9], 0, v[24:25]
	s_nop 0
	v_lshlrev_b32_e32 v32, 16, v152
	v_and_b32_e32 v33, 0xffff0000, v152
	v_lshlrev_b32_e32 v10, 16, v153
	v_and_b32_e32 v11, 0xffff0000, v153
	v_lshlrev_b32_e32 v34, 16, v154
	v_and_b32_e32 v35, 0xffff0000, v154
	v_lshlrev_b32_e32 v12, 16, v155
	v_and_b32_e32 v13, 0xffff0000, v155
	v_mul_f32_e32 v36, 0xbfb8aa3b, v32
	v_mul_f32_e32 v37, 0xbfb8aa3b, v33
	v_mul_f32_e32 v38, 0xbfb8aa3b, v10
	v_mul_f32_e32 v39, 0xbfb8aa3b, v11
	v_mul_f32_e32 v40, 0xbfb8aa3b, v34
	v_mul_f32_e32 v41, 0xbfb8aa3b, v35
	v_mul_f32_e32 v42, 0xbfb8aa3b, v12
	v_mul_f32_e32 v43, 0xbfb8aa3b, v13
	v_exp_f32_e32 v36, v36
	v_exp_f32_e32 v37, v37
	v_exp_f32_e32 v38, v38
	v_exp_f32_e32 v39, v39
	v_exp_f32_e32 v40, v40
	v_exp_f32_e32 v41, v41
	v_exp_f32_e32 v42, v42
	v_exp_f32_e32 v43, v43
	v_add_f32_e32 v36, 1.0, v36
	v_add_f32_e32 v37, 1.0, v37
	v_add_f32_e32 v38, 1.0, v38
	v_add_f32_e32 v39, 1.0, v39
	v_add_f32_e32 v40, 1.0, v40
	v_add_f32_e32 v41, 1.0, v41
	v_add_f32_e32 v42, 1.0, v42
	v_add_f32_e32 v43, 1.0, v43
	v_rcp_f32_e32 v36, v36
	v_rcp_f32_e32 v37, v37
	v_rcp_f32_e32 v38, v38
	v_rcp_f32_e32 v39, v39
	v_rcp_f32_e32 v40, v40
	v_rcp_f32_e32 v41, v41
	v_rcp_f32_e32 v42, v42
	v_rcp_f32_e32 v43, v43
	v_pk_mul_f32 v[32:33], v[36:37], v[32:33]
	v_pk_mul_f32 v[10:11], v[38:39], v[10:11]
	v_pk_mul_f32 v[34:35], v[40:41], v[34:35]
	v_pk_mul_f32 v[12:13], v[42:43], v[12:13]
	v_pk_mul_f32 v[28:29], v[32:33], v[28:29]
	v_pk_mul_f32 v[0:1], v[10:11], v[0:1]
	v_pk_mul_f32 v[10:11], v[34:35], v[30:31]
	v_pk_mul_f32 v[2:3], v[12:13], v[2:3]
	s_nop 0
	v_pk_mul_f32 v[12:13], v[164:165], v[28:29]
	v_pk_mul_f32 v[14:15], v[166:167], v[0:1]
	s_nop 0
	v_pk_mul_f32 v[10:11], v[168:169], v[10:11]
	v_pk_mul_f32 v[16:17], v[170:171], v[2:3]
	v_cvt_pk_bf16_f32 v0, v12, v13
	v_cvt_pk_bf16_f32 v1, v14, v15
	v_cvt_pk_bf16_f32 v2, v10, v11
	v_cvt_pk_bf16_f32 v3, v16, v17
	global_store_dwordx4 v[22:23], v[0:3], off
	s_nop 1
	s_waitcnt vmcnt(7)
	s_nop 0
	ds_read_b128 v[18:21], v129 offset:47488
	v_mov_b32_e32 v23, s25
	v_or_b32_e32 v22, s24, v124
	v_lshlrev_b64 v[26:27], 11, v[22:23]
	v_lshl_add_u64 v[28:29], v[4:5], 0, v[24:25]
	ds_read_b128 v[22:25], v129 offset:48576
	s_waitcnt lgkmcnt(1)
	v_lshlrev_b32_e32 v30, 16, v18
	v_and_b32_e32 v31, 0xffff0000, v18
	v_lshlrev_b32_e32 v18, 16, v19
	v_and_b32_e32 v19, 0xffff0000, v19
	v_lshlrev_b32_e32 v32, 16, v20
	v_and_b32_e32 v33, 0xffff0000, v20
	v_lshlrev_b32_e32 v20, 16, v21
	v_and_b32_e32 v21, 0xffff0000, v21
	v_lshl_add_u64 v[8:9], v[8:9], 0, v[26:27]
	v_lshl_add_u64 v[4:5], v[4:5], 0, v[26:27]
	s_nop 0
	v_lshlrev_b32_e32 v34, 16, v156
	v_and_b32_e32 v35, 0xffff0000, v156
	v_lshlrev_b32_e32 v0, 16, v157
	v_and_b32_e32 v1, 0xffff0000, v157
	v_lshlrev_b32_e32 v36, 16, v158
	v_and_b32_e32 v37, 0xffff0000, v158
	v_lshlrev_b32_e32 v2, 16, v159
	v_and_b32_e32 v3, 0xffff0000, v159
	v_mul_f32_e32 v38, 0xbfb8aa3b, v34
	v_mul_f32_e32 v39, 0xbfb8aa3b, v35
	v_mul_f32_e32 v40, 0xbfb8aa3b, v0
	v_mul_f32_e32 v41, 0xbfb8aa3b, v1
	v_mul_f32_e32 v42, 0xbfb8aa3b, v36
	v_mul_f32_e32 v43, 0xbfb8aa3b, v37
	v_mul_f32_e32 v44, 0xbfb8aa3b, v2
	v_mul_f32_e32 v45, 0xbfb8aa3b, v3
	v_exp_f32_e32 v38, v38
	v_exp_f32_e32 v39, v39
	v_exp_f32_e32 v40, v40
	v_exp_f32_e32 v41, v41
	v_exp_f32_e32 v42, v42
	v_exp_f32_e32 v43, v43
	v_exp_f32_e32 v44, v44
	v_exp_f32_e32 v45, v45
	v_add_f32_e32 v38, 1.0, v38
	v_add_f32_e32 v39, 1.0, v39
	v_add_f32_e32 v40, 1.0, v40
	v_add_f32_e32 v41, 1.0, v41
	v_add_f32_e32 v42, 1.0, v42
	v_add_f32_e32 v43, 1.0, v43
	v_add_f32_e32 v44, 1.0, v44
	v_add_f32_e32 v45, 1.0, v45
	v_rcp_f32_e32 v38, v38
	v_rcp_f32_e32 v39, v39
	v_rcp_f32_e32 v40, v40
	v_rcp_f32_e32 v41, v41
	v_rcp_f32_e32 v42, v42
	v_rcp_f32_e32 v43, v43
	v_rcp_f32_e32 v44, v44
	v_rcp_f32_e32 v45, v45
	v_pk_mul_f32 v[34:35], v[38:39], v[34:35]
	v_pk_mul_f32 v[0:1], v[40:41], v[0:1]
	v_pk_mul_f32 v[36:37], v[42:43], v[36:37]
	v_pk_mul_f32 v[2:3], v[44:45], v[2:3]
	v_pk_mul_f32 v[30:31], v[34:35], v[30:31]
	v_pk_mul_f32 v[0:1], v[0:1], v[18:19]
	v_pk_mul_f32 v[18:19], v[36:37], v[32:33]
	v_pk_mul_f32 v[2:3], v[2:3], v[20:21]
	s_nop 0
	v_pk_mul_f32 v[10:11], v[164:165], v[30:31]
	v_pk_mul_f32 v[12:13], v[166:167], v[0:1]
	s_nop 0
	v_pk_mul_f32 v[14:15], v[168:169], v[18:19]
	v_pk_mul_f32 v[16:17], v[170:171], v[2:3]
	v_cvt_pk_bf16_f32 v0, v10, v11
	v_cvt_pk_bf16_f32 v1, v12, v13
	v_cvt_pk_bf16_f32 v2, v14, v15
	v_cvt_pk_bf16_f32 v3, v16, v17
	global_store_dwordx4 v[28:29], v[0:3], off
	s_nop 1
	s_waitcnt vmcnt(7)
	s_nop 0
	s_waitcnt lgkmcnt(0)
	v_lshlrev_b32_e32 v6, 16, v22
	v_and_b32_e32 v7, 0xffff0000, v22
	v_lshlrev_b32_e32 v16, 16, v23
	v_and_b32_e32 v17, 0xffff0000, v23
	v_lshlrev_b32_e32 v18, 16, v24
	v_and_b32_e32 v19, 0xffff0000, v24
	v_lshlrev_b32_e32 v20, 16, v25
	v_and_b32_e32 v21, 0xffff0000, v25
	s_nop 0
	v_lshlrev_b32_e32 v22, 16, v160
	v_and_b32_e32 v23, 0xffff0000, v160
	v_lshlrev_b32_e32 v0, 16, v161
	v_and_b32_e32 v1, 0xffff0000, v161
	v_lshlrev_b32_e32 v24, 16, v162
	v_and_b32_e32 v25, 0xffff0000, v162
	v_lshlrev_b32_e32 v2, 16, v163
	v_and_b32_e32 v3, 0xffff0000, v163
	v_mul_f32_e32 v26, 0xbfb8aa3b, v22
	v_mul_f32_e32 v27, 0xbfb8aa3b, v23
	v_mul_f32_e32 v28, 0xbfb8aa3b, v0
	v_mul_f32_e32 v29, 0xbfb8aa3b, v1
	v_mul_f32_e32 v30, 0xbfb8aa3b, v24
	v_mul_f32_e32 v31, 0xbfb8aa3b, v25
	v_mul_f32_e32 v32, 0xbfb8aa3b, v2
	v_mul_f32_e32 v33, 0xbfb8aa3b, v3
	v_exp_f32_e32 v26, v26
	v_exp_f32_e32 v27, v27
	v_exp_f32_e32 v28, v28
	v_exp_f32_e32 v29, v29
	v_exp_f32_e32 v30, v30
	v_exp_f32_e32 v31, v31
	v_exp_f32_e32 v32, v32
	v_exp_f32_e32 v33, v33
	v_add_f32_e32 v26, 1.0, v26
	v_add_f32_e32 v27, 1.0, v27
	v_add_f32_e32 v28, 1.0, v28
	v_add_f32_e32 v29, 1.0, v29
	v_add_f32_e32 v30, 1.0, v30
	v_add_f32_e32 v31, 1.0, v31
	v_add_f32_e32 v32, 1.0, v32
	v_add_f32_e32 v33, 1.0, v33
	v_rcp_f32_e32 v26, v26
	v_rcp_f32_e32 v27, v27
	v_rcp_f32_e32 v28, v28
	v_rcp_f32_e32 v29, v29
	v_rcp_f32_e32 v30, v30
	v_rcp_f32_e32 v31, v31
	v_rcp_f32_e32 v32, v32
	v_rcp_f32_e32 v33, v33
	v_pk_mul_f32 v[22:23], v[26:27], v[22:23]
	v_pk_mul_f32 v[0:1], v[28:29], v[0:1]
	v_pk_mul_f32 v[24:25], v[30:31], v[24:25]
	v_pk_mul_f32 v[2:3], v[32:33], v[2:3]
	v_pk_mul_f32 v[6:7], v[22:23], v[6:7]
	v_pk_mul_f32 v[0:1], v[0:1], v[16:17]
	v_pk_mul_f32 v[16:17], v[24:25], v[18:19]
	v_pk_mul_f32 v[2:3], v[2:3], v[20:21]
	s_nop 0
	v_pk_mul_f32 v[6:7], v[164:165], v[6:7]
	v_pk_mul_f32 v[8:9], v[166:167], v[0:1]
	s_nop 0
	v_pk_mul_f32 v[10:11], v[168:169], v[16:17]
	v_pk_mul_f32 v[12:13], v[170:171], v[2:3]
	v_cvt_pk_bf16_f32 v0, v6, v7
	v_cvt_pk_bf16_f32 v1, v8, v9
	v_cvt_pk_bf16_f32 v2, v10, v11
	v_cvt_pk_bf16_f32 v3, v12, v13
	global_store_dwordx4 v[4:5], v[0:3], off
	s_cbranch_scc0 .LBB0_1210
